# PEER table rows of layers 1-3 converted by the idle waves 4-7 of the RWKV scan phase (hand-written, same fp8 layout and power-of-two row scale); removed from the layer-1/2 scores phases
# speedup vs baseline: 1.0735x; 1.0046x over previous
; __device__ __forceinline__ void peer_convert_rows(KP P, const Ctx& c, int g_lo, int g_hi, int rank, int nranks) {
;     unsigned char* ws = P->ws;
;     f32x4 xn[2][8];
;     ...
;     { const int gf = g_lo + (rank * 8 + c.wave) * 2; if (gf < g_hi) CV_LOAD(gf); }
;     for (int g0 = g_lo + (rank * 8 + c.wave) * 2; g0 < g_hi; g0 += nranks * 16) {
;         f32x4 x[2][8]; float am[2] = {0.f, 0.f};
; #pragma unroll
;         for (int h = 0; h < 2; ++h)
; #pragma unroll
;             for (int q = 0; q < 8; ++q) x[h][q] = xn[h][q];
;         if (g0 + nranks * 16 < g_hi) CV_LOAD(g0 + nranks * 16);
; #pragma unroll
;         for (int h = 0; h < 2; ++h) { if (g0 + h >= g_hi) break;
;             const int g = g0 + h; const int lt = g >> 14, e = g & 16383, layer = lt >> 1, t = lt & 1;
; #pragma unroll
;             for (int q = 0; q < 8; ++q) am[h] = fmaxf(am[h], fmaxf(fmaxf(fabsf(x[h][q][0]), fabsf(x[h][q][1])), fmaxf(fabsf(x[h][q][2]), fabsf(x[h][q][3]))));
;             const float a = wave_max(am[h]);
;             const float sc = a > 0.f ? exp2f(floorf(log2f(384.0f / a))) : 1.0f;
;             if (c.lane == 0) ((float*)(ws + WS_PSC))[(size_t)t * 4 * 16384 + layer * 16384 + e] = 1.0f / sc;
;             unsigned char* dst = ws + (t ? WS_PV : WS_PU) + (size_t)layer * 16384 * D;
; #pragma unroll
;             for (int jj = 0; jj < 2; ++jj) { u32x4 o;
; #pragma unroll
;                 for (int w = 0; w < 4; ++w) { const f32x4 v = x[h][jj * 4 + w] * sc; int p = 0; p = __builtin_amdgcn_cvt_pk_fp8_f32(v[0], v[1], p, false); p = __builtin_amdgcn_cvt_pk_fp8_f32(v[2], v[3], p, true); o[w] = (unsigned)p; }
;                 const int db = (c.lane >> 3) + 8 * jj;
;                 *(u32x4*)(dst + ((size_t)db * 16384 + e) * 128 + (c.lane & 7) * 16) = o; } } }
;     ...
; }
.Lrw_cv:
	v_readlane_b32 s60, v244, 4
	s_cmpk_lg_i32 s60, 0x100
	s_cbranch_scc1 .LBB0_1754
	s_lshr_b32 s61, s63, 6
	s_sub_i32 s61, s61, 4
	s_lshl_b32 s62, s2, 2
	s_add_i32 s61, s61, s62
	s_lshl_b32 s62, s8, 10
	s_add_i32 s61, s61, s62
	s_lshl_b32 s61, s61, 1
	s_add_i32 s61, s61, 0xaaab
	s_cmp_ge_u32 s61, 0x20000
	s_cbranch_scc1 .LBB0_1754
	s_load_dwordx4 s[64:67], s[94:95], 0x50
	s_load_dwordx2 s[68:69], s[94:95], 0x130
	v_and_b32_e32 v102, 63, v0
	v_lshlrev_b32_e32 v103, 6, v102
	v_add_u32_e32 v104, 0x1000, v103
	v_lshrrev_b32_e32 v105, 3, v102
	v_and_b32_e32 v106, 7, v102
	v_lshlrev_b32_e32 v105, 21, v105
	v_lshl_or_b32 v105, v106, 4, v105
	v_add_u32_e32 v106, 0x1000000, v105
	v_mov_b32_e32 v204, 1.0
	v_mov_b32_e32 v206, 0
	s_add_i32 s70, s61, 1
	s_cmp_lt_u32 s70, 0x20000
	s_cselect_b32 s88, 1, 0
	s_waitcnt lgkmcnt(0)
	s_lshr_b32 s71, s61, 14
	s_and_b32 s72, s61, 0x3fff
	s_lshr_b32 s73, s71, 1
	s_and_b32 s74, s71, 1
	s_cmp_eq_u32 s74, 0
	s_cselect_b32 s76, s64, s66
	s_cselect_b32 s77, s65, s67
	s_lshl_b32 s75, s73, 14
	s_add_i32 s75, s75, s72
	s_lshl_b32 s75, s75, 13
	s_add_u32 s76, s76, s75
	s_addc_u32 s77, s77, 0
	global_load_dwordx4 v[38:41], v103, s[76:77]
	global_load_dwordx4 v[42:45], v103, s[76:77] offset:16
	global_load_dwordx4 v[46:49], v103, s[76:77] offset:32
	global_load_dwordx4 v[50:53], v103, s[76:77] offset:48
	global_load_dwordx4 v[54:57], v104, s[76:77]
	global_load_dwordx4 v[58:61], v104, s[76:77] offset:16
	global_load_dwordx4 v[62:65], v104, s[76:77] offset:32
	global_load_dwordx4 v[66:69], v104, s[76:77] offset:48
	s_cmp_eq_u32 s88, 0
	s_cbranch_scc1 .Lrw_cv_l1
	s_lshr_b32 s71, s70, 14
	s_and_b32 s72, s70, 0x3fff
	s_lshr_b32 s73, s71, 1
	s_and_b32 s74, s71, 1
	s_cmp_eq_u32 s74, 0
	s_cselect_b32 s78, s64, s66
	s_cselect_b32 s79, s65, s67
	s_lshl_b32 s75, s73, 14
	s_add_i32 s75, s75, s72
	s_lshl_b32 s75, s75, 13
	s_add_u32 s78, s78, s75
	s_addc_u32 s79, s79, 0
	global_load_dwordx4 v[70:73], v103, s[78:79]
	global_load_dwordx4 v[74:77], v103, s[78:79] offset:16
	global_load_dwordx4 v[78:81], v103, s[78:79] offset:32
	global_load_dwordx4 v[82:85], v103, s[78:79] offset:48
	global_load_dwordx4 v[86:89], v104, s[78:79]
	global_load_dwordx4 v[90:93], v104, s[78:79] offset:16
	global_load_dwordx4 v[94:97], v104, s[78:79] offset:32
	global_load_dwordx4 v[98:101], v104, s[78:79] offset:48
.Lrw_cv_l1:
	s_waitcnt vmcnt(0)
	v_max3_f32 v201, |v38|, |v39|, |v40|
	v_max3_f32 v201, v201, |v41|, |v42|
	v_max3_f32 v201, v201, |v43|, |v44|
	v_max3_f32 v201, v201, |v45|, |v46|
	v_max3_f32 v201, v201, |v47|, |v48|
	v_max3_f32 v201, v201, |v49|, |v50|
	v_max3_f32 v201, v201, |v51|, |v52|
	v_max3_f32 v201, v201, |v53|, |v54|
	v_max3_f32 v201, v201, |v55|, |v56|
	v_max3_f32 v201, v201, |v57|, |v58|
	v_max3_f32 v201, v201, |v59|, |v60|
	v_max3_f32 v201, v201, |v61|, |v62|
	v_max3_f32 v201, v201, |v63|, |v64|
	v_max3_f32 v201, v201, |v65|, |v66|
	v_max3_f32 v201, v201, |v67|, |v68|
	v_max_f32_e64 v201, v201, |v69|
	s_nop 1
	v_max_f32_dpp v201, v201, v201 quad_perm:[1,0,3,2] row_mask:0xf bank_mask:0xf
	s_nop 1
	v_max_f32_dpp v201, v201, v201 quad_perm:[2,3,0,1] row_mask:0xf bank_mask:0xf
	s_nop 1
	v_max_f32_dpp v201, v201, v201 row_half_mirror row_mask:0xf bank_mask:0xf
	s_nop 1
	v_max_f32_dpp v201, v201, v201 row_mirror row_mask:0xf bank_mask:0xf
	s_lshr_b32 s71, s61, 14
	s_and_b32 s72, s61, 0x3fff
	v_readlane_b32 s80, v201, 0
	v_readlane_b32 s81, v201, 16
	v_readlane_b32 s82, v201, 32
	v_readlane_b32 s83, v201, 48
	s_lshr_b32 s73, s71, 1
	s_and_b32 s74, s71, 1
	s_lshl_b32 s75, s74, 27
	s_add_i32 s75, s75, 0x10000000
	s_lshl_b32 s62, s73, 25
	s_add_i32 s75, s75, s62
	s_lshl_b32 s62, s72, 7
	s_add_i32 s75, s75, s62
	s_add_u32 s86, s68, s75
	s_addc_u32 s87, s69, 0
	s_lshl_b32 s75, s74, 2
	s_add_i32 s75, s75, s73
	s_lshl_b32 s75, s75, 14
	s_add_i32 s75, s75, s72
	s_lshl_b32 s75, s75, 2
	s_add_i32 s75, s75, 0x20000000
	s_add_u32 s84, s68, s75
	s_addc_u32 s85, s69, 0
	v_mov_b32_e32 v200, s80
	v_max_f32_e32 v200, s81, v200
	v_max_f32_e32 v200, s82, v200
	v_max_f32_e32 v200, s83, v200
	v_rcp_f32_e32 v202, v200
	v_cmp_lt_f32_e32 vcc, 0, v200
	v_mul_f32_e32 v202, 0x43c00000, v202
	v_min_f32_e32 v202, 0x7e800000, v202
	v_and_b32_e32 v202, 0x7f800000, v202
	v_cndmask_b32_e32 v202, v204, v202, vcc
	v_sub_u32_e32 v205, 0x7f000000, v202
	v_pk_mul_f32 v[38:39], v[38:39], v[202:203] op_sel_hi:[1,0]
	v_pk_mul_f32 v[40:41], v[40:41], v[202:203] op_sel_hi:[1,0]
	v_pk_mul_f32 v[42:43], v[42:43], v[202:203] op_sel_hi:[1,0]
	v_pk_mul_f32 v[44:45], v[44:45], v[202:203] op_sel_hi:[1,0]
	v_pk_mul_f32 v[46:47], v[46:47], v[202:203] op_sel_hi:[1,0]
	v_pk_mul_f32 v[48:49], v[48:49], v[202:203] op_sel_hi:[1,0]
	v_pk_mul_f32 v[50:51], v[50:51], v[202:203] op_sel_hi:[1,0]
	v_pk_mul_f32 v[52:53], v[52:53], v[202:203] op_sel_hi:[1,0]
	v_pk_mul_f32 v[54:55], v[54:55], v[202:203] op_sel_hi:[1,0]
	v_pk_mul_f32 v[56:57], v[56:57], v[202:203] op_sel_hi:[1,0]
	v_pk_mul_f32 v[58:59], v[58:59], v[202:203] op_sel_hi:[1,0]
	v_pk_mul_f32 v[60:61], v[60:61], v[202:203] op_sel_hi:[1,0]
	v_pk_mul_f32 v[62:63], v[62:63], v[202:203] op_sel_hi:[1,0]
	v_pk_mul_f32 v[64:65], v[64:65], v[202:203] op_sel_hi:[1,0]
	v_pk_mul_f32 v[66:67], v[66:67], v[202:203] op_sel_hi:[1,0]
	v_pk_mul_f32 v[68:69], v[68:69], v[202:203] op_sel_hi:[1,0]
	v_cvt_pk_fp8_f32 v208, v38, v39
	v_cvt_pk_fp8_f32 v209, v42, v43
	v_cvt_pk_fp8_f32 v210, v46, v47
	v_cvt_pk_fp8_f32 v211, v50, v51
	v_cvt_pk_fp8_f32 v212, v54, v55
	v_cvt_pk_fp8_f32 v213, v58, v59
	v_cvt_pk_fp8_f32 v214, v62, v63
	v_cvt_pk_fp8_f32 v215, v66, v67
	v_cvt_pk_fp8_f32 v208, v40, v41 op_sel:[0,0,1]
	v_cvt_pk_fp8_f32 v209, v44, v45 op_sel:[0,0,1]
	v_cvt_pk_fp8_f32 v210, v48, v49 op_sel:[0,0,1]
	v_cvt_pk_fp8_f32 v211, v52, v53 op_sel:[0,0,1]
	v_cvt_pk_fp8_f32 v212, v56, v57 op_sel:[0,0,1]
	v_cvt_pk_fp8_f32 v213, v60, v61 op_sel:[0,0,1]
	v_cvt_pk_fp8_f32 v214, v64, v65 op_sel:[0,0,1]
	v_cvt_pk_fp8_f32 v215, v68, v69 op_sel:[0,0,1]
	global_store_dwordx4 v105, v[208:211], s[86:87]
	global_store_dwordx4 v106, v[212:215], s[86:87]
	s_mov_b64 exec, 1
	global_store_dword v206, v205, s[84:85]
	s_mov_b64 exec, -1
	s_cmp_eq_u32 s88, 0
	s_cbranch_scc1 .LBB0_1754
; __device__ __forceinline__ void peer_convert_rows(KP P, const Ctx& c, int g_lo, int g_hi, int rank, int nranks) {
;     ...
;         if (g0 + nranks * 16 < g_hi) CV_LOAD(g0 + nranks * 16);
; #pragma unroll
;         for (int h = 0; h < 2; ++h) { if (g0 + h >= g_hi) break;
;             const int g = g0 + h; const int lt = g >> 14, e = g & 16383, layer = lt >> 1, t = lt & 1;
; #pragma unroll
;             for (int q = 0; q < 8; ++q) am[h] = fmaxf(am[h], fmaxf(fmaxf(fabsf(x[h][q][0]), fabsf(x[h][q][1])), fmaxf(fabsf(x[h][q][2]), fabsf(x[h][q][3]))));
;             const float a = wave_max(am[h]);
;             const float sc = a > 0.f ? exp2f(floorf(log2f(384.0f / a))) : 1.0f;
;             if (c.lane == 0) ((float*)(ws + WS_PSC))[(size_t)t * 4 * 16384 + layer * 16384 + e] = 1.0f / sc;
;             unsigned char* dst = ws + (t ? WS_PV : WS_PU) + (size_t)layer * 16384 * D;
; #pragma unroll
;             for (int jj = 0; jj < 2; ++jj) { u32x4 o;
; #pragma unroll
;                 for (int w = 0; w < 4; ++w) { const f32x4 v = x[h][jj * 4 + w] * sc; int p = 0; p = __builtin_amdgcn_cvt_pk_fp8_f32(v[0], v[1], p, false); p = __builtin_amdgcn_cvt_pk_fp8_f32(v[2], v[3], p, true); o[w] = (unsigned)p; }
;                 const int db = (c.lane >> 3) + 8 * jj;
;                 *(u32x4*)(dst + ((size_t)db * 16384 + e) * 128 + (c.lane & 7) * 16) = o; } } }
	v_max3_f32 v201, |v70|, |v71|, |v72|
	v_max3_f32 v201, v201, |v73|, |v74|
	v_max3_f32 v201, v201, |v75|, |v76|
	v_max3_f32 v201, v201, |v77|, |v78|
	v_max3_f32 v201, v201, |v79|, |v80|
	v_max3_f32 v201, v201, |v81|, |v82|
	v_max3_f32 v201, v201, |v83|, |v84|
	v_max3_f32 v201, v201, |v85|, |v86|
	v_max3_f32 v201, v201, |v87|, |v88|
	v_max3_f32 v201, v201, |v89|, |v90|
	v_max3_f32 v201, v201, |v91|, |v92|
	v_max3_f32 v201, v201, |v93|, |v94|
	v_max3_f32 v201, v201, |v95|, |v96|
	v_max3_f32 v201, v201, |v97|, |v98|
	v_max3_f32 v201, v201, |v99|, |v100|
	v_max_f32_e64 v201, v201, |v101|
	s_nop 1
	v_max_f32_dpp v201, v201, v201 quad_perm:[1,0,3,2] row_mask:0xf bank_mask:0xf
	s_nop 1
	v_max_f32_dpp v201, v201, v201 quad_perm:[2,3,0,1] row_mask:0xf bank_mask:0xf
	s_nop 1
	v_max_f32_dpp v201, v201, v201 row_half_mirror row_mask:0xf bank_mask:0xf
	s_nop 1
	v_max_f32_dpp v201, v201, v201 row_mirror row_mask:0xf bank_mask:0xf
	s_lshr_b32 s71, s70, 14
	s_and_b32 s72, s70, 0x3fff
	v_readlane_b32 s80, v201, 0
	v_readlane_b32 s81, v201, 16
	v_readlane_b32 s82, v201, 32
	v_readlane_b32 s83, v201, 48
	s_lshr_b32 s73, s71, 1
	s_and_b32 s74, s71, 1
	s_lshl_b32 s75, s74, 27
	s_add_i32 s75, s75, 0x10000000
	s_lshl_b32 s62, s73, 25
	s_add_i32 s75, s75, s62
	s_lshl_b32 s62, s72, 7
	s_add_i32 s75, s75, s62
	s_add_u32 s86, s68, s75
	s_addc_u32 s87, s69, 0
	s_lshl_b32 s75, s74, 2
	s_add_i32 s75, s75, s73
	s_lshl_b32 s75, s75, 14
	s_add_i32 s75, s75, s72
	s_lshl_b32 s75, s75, 2
	s_add_i32 s75, s75, 0x20000000
	s_add_u32 s84, s68, s75
	s_addc_u32 s85, s69, 0
	v_mov_b32_e32 v200, s80
	v_max_f32_e32 v200, s81, v200
	v_max_f32_e32 v200, s82, v200
	v_max_f32_e32 v200, s83, v200
	v_rcp_f32_e32 v202, v200
	v_cmp_lt_f32_e32 vcc, 0, v200
	v_mul_f32_e32 v202, 0x43c00000, v202
	v_min_f32_e32 v202, 0x7e800000, v202
	v_and_b32_e32 v202, 0x7f800000, v202
	v_cndmask_b32_e32 v202, v204, v202, vcc
	v_sub_u32_e32 v205, 0x7f000000, v202
	v_pk_mul_f32 v[70:71], v[70:71], v[202:203] op_sel_hi:[1,0]
	v_pk_mul_f32 v[72:73], v[72:73], v[202:203] op_sel_hi:[1,0]
	v_pk_mul_f32 v[74:75], v[74:75], v[202:203] op_sel_hi:[1,0]
	v_pk_mul_f32 v[76:77], v[76:77], v[202:203] op_sel_hi:[1,0]
	v_pk_mul_f32 v[78:79], v[78:79], v[202:203] op_sel_hi:[1,0]
	v_pk_mul_f32 v[80:81], v[80:81], v[202:203] op_sel_hi:[1,0]
	v_pk_mul_f32 v[82:83], v[82:83], v[202:203] op_sel_hi:[1,0]
	v_pk_mul_f32 v[84:85], v[84:85], v[202:203] op_sel_hi:[1,0]
	v_pk_mul_f32 v[86:87], v[86:87], v[202:203] op_sel_hi:[1,0]
	v_pk_mul_f32 v[88:89], v[88:89], v[202:203] op_sel_hi:[1,0]
	v_pk_mul_f32 v[90:91], v[90:91], v[202:203] op_sel_hi:[1,0]
	v_pk_mul_f32 v[92:93], v[92:93], v[202:203] op_sel_hi:[1,0]
	v_pk_mul_f32 v[94:95], v[94:95], v[202:203] op_sel_hi:[1,0]
	v_pk_mul_f32 v[96:97], v[96:97], v[202:203] op_sel_hi:[1,0]
	v_pk_mul_f32 v[98:99], v[98:99], v[202:203] op_sel_hi:[1,0]
	v_pk_mul_f32 v[100:101], v[100:101], v[202:203] op_sel_hi:[1,0]
	v_cvt_pk_fp8_f32 v216, v70, v71
	v_cvt_pk_fp8_f32 v217, v74, v75
	v_cvt_pk_fp8_f32 v218, v78, v79
	v_cvt_pk_fp8_f32 v219, v82, v83
	v_cvt_pk_fp8_f32 v220, v86, v87
	v_cvt_pk_fp8_f32 v221, v90, v91
	v_cvt_pk_fp8_f32 v222, v94, v95
	v_cvt_pk_fp8_f32 v223, v98, v99
	v_cvt_pk_fp8_f32 v216, v72, v73 op_sel:[0,0,1]
	v_cvt_pk_fp8_f32 v217, v76, v77 op_sel:[0,0,1]
	v_cvt_pk_fp8_f32 v218, v80, v81 op_sel:[0,0,1]
	v_cvt_pk_fp8_f32 v219, v84, v85 op_sel:[0,0,1]
	v_cvt_pk_fp8_f32 v220, v88, v89 op_sel:[0,0,1]
	v_cvt_pk_fp8_f32 v221, v92, v93 op_sel:[0,0,1]
	v_cvt_pk_fp8_f32 v222, v96, v97 op_sel:[0,0,1]
	v_cvt_pk_fp8_f32 v223, v100, v101 op_sel:[0,0,1]
	global_store_dwordx4 v105, v[216:219], s[86:87]
	global_store_dwordx4 v106, v[220:223], s[86:87]
	s_mov_b64 exec, 1
	global_store_dword v206, v205, s[84:85]
	s_mov_b64 exec, -1
	s_branch .LBB0_1754

; #define PROBE_REP(bit) for (int _rep = 0; _rep < (((PROBE) >> (bit)) & 1) + 1; ++_rep)
; __device__ __forceinline__ KP kp_fresh() { KP p = (KP)__builtin_amdgcn_kernarg_segment_ptr(); asm volatile("" : "+s"(p)); return p; }
; #define GRID_BAR() xcd_barrier(bar)
; template <int LAYER, bool LAST> __device__ __forceinline__ void peer_phases(LAS unsigned char* lds, const XcdBarrier& bar) {
;     ...
;     PROBE_REP(2) { KP P = kp_fresh(); unsigned char* ws = P->ws; GPlain g{(const bf16_t*)(ws + WS_H2), (const bf16_t*)(ws + WS_WQ) + (size_t)LAYER * D * D, D, D, D}; EpiF32Plain E{(float*)(ws + WS_S), D}; run_gemm(lds, g, D, E, LAST ? 4 : 0);
;         if (!LAST && _rep == 0) { constexpr int NR = 8 * 16384, SH = (NR + 2) / 3; const int lo = LAYER * SH, hi = (LAYER == 2) ? NR : (LAYER + 1) * SH;
;             if ((int)gridDim.x == 256) { if ((int)blockIdx.x >= 32) peer_convert_rows(kp_fresh(), make_ctx(lds), lo, hi, (int)blockIdx.x - 32, 224); }
;             else peer_convert_rows(kp_fresh(), make_ctx(lds), lo, hi, (int)blockIdx.x, (int)gridDim.x); }
;         GRID_BAR(); }
.LBB0_2026:
	s_andn2_b64 vcc, exec, s[0:1]
	s_cbranch_vccnz .LBB0_2043
	v_readlane_b32 s0, v239, 25
	v_readlane_b32 s1, v239, 26
	s_and_b64 vcc, exec, s[0:1]
	s_cbranch_vccnz .LBB0_2043
	s_branch .LBB0_2043
